# attnaddr + attention fast-path bias constant selected with s_cselect_b32 (SGPR operand) instead of 2 v_mov + v_cndmask
# baseline (speedup 1.0000x reference)
; __device__ __forceinline__ void partialSM(f32x16& p0, f32x16& p1, float& m_reg, float& mn, float& alpha, int kt0, int qpos, int qw, int hi, const float* tb2, float cL, float cR) {
;     ...
;   const int rel_hi = kt0 + 63 - qw, rel_lo = kt0 - (qw + 31);
;   if (rel_hi <= -91 || rel_lo >= 91) {
;     const float cm = ((rel_hi <= -91) ? cL : cR) - m_reg;
; #pragma unroll
;     for (int r = 0; r < 16; ++r) { p0[r] = fmaf(p0[r], C1, cm); p1[r] = fmaf(p1[r], C1, cm); }
.LBB0_303:
	s_andn2_b64 vcc, exec, s[0:1]
	s_cbranch_vccnz .LBB0_305
	s_cmpk_lt_i32 s65, 0xffa6
	s_cselect_b32 s69, s61, s62
	v_sub_f32_e32 v80, s69, v0
	v_pk_fma_f32 v[142:143], v[126:127], s[6:7], v[80:81] op_sel_hi:[1,0,0]
	v_pk_fma_f32 v[140:141], v[124:125], s[6:7], v[80:81] op_sel_hi:[1,0,0]
	v_pk_fma_f32 v[138:139], v[122:123], s[6:7], v[80:81] op_sel_hi:[1,0,0]
	v_pk_fma_f32 v[136:137], v[120:121], s[6:7], v[80:81] op_sel_hi:[1,0,0]
	v_pk_fma_f32 v[134:135], v[118:119], s[6:7], v[80:81] op_sel_hi:[1,0,0]
	v_pk_fma_f32 v[132:133], v[116:117], s[6:7], v[80:81] op_sel_hi:[1,0,0]
	v_pk_fma_f32 v[130:131], v[114:115], s[6:7], v[80:81] op_sel_hi:[1,0,0]
	v_pk_fma_f32 v[128:129], v[112:113], s[6:7], v[80:81] op_sel_hi:[1,0,0]
	v_pk_fma_f32 v[94:95], v[110:111], s[6:7], v[80:81] op_sel_hi:[1,0,0]
	v_pk_fma_f32 v[92:93], v[108:109], s[6:7], v[80:81] op_sel_hi:[1,0,0]
	v_pk_fma_f32 v[90:91], v[106:107], s[6:7], v[80:81] op_sel_hi:[1,0,0]
	v_pk_fma_f32 v[88:89], v[104:105], s[6:7], v[80:81] op_sel_hi:[1,0,0]
	v_pk_fma_f32 v[86:87], v[102:103], s[6:7], v[80:81] op_sel_hi:[1,0,0]
	v_pk_fma_f32 v[84:85], v[100:101], s[6:7], v[80:81] op_sel_hi:[1,0,0]
	v_pk_fma_f32 v[82:83], v[98:99], s[6:7], v[80:81] op_sel_hi:[1,0,0]
	v_pk_fma_f32 v[80:81], v[96:97], s[6:7], v[80:81] op_sel_hi:[1,0,0]

; __device__ __forceinline__ void partialSM(f32x16& p0, f32x16& p1, float& m_reg, float& mn, float& alpha, int kt0, int qpos, int qw, int hi, const float* tb2, float cL, float cR) {
;     ...
;   const int rel_hi = kt0 + 63 - qw, rel_lo = kt0 - (qw + 31);
;   if (rel_hi <= -91 || rel_lo >= 91) {
;     const float cm = ((rel_hi <= -91) ? cL : cR) - m_reg;
; #pragma unroll
;     for (int r = 0; r < 16; ++r) { p0[r] = fmaf(p0[r], C1, cm); p1[r] = fmaf(p1[r], C1, cm); }
.LBB0_309:
	s_andn2_b64 vcc, exec, s[26:27]
	s_cbranch_vccnz .LBB0_311
	s_add_i32 s5, s65, 64
	s_cmpk_lt_i32 s5, 0xffa6
	s_cselect_b32 s69, s61, s62
	v_sub_f32_e32 v80, s69, v0
	v_pk_fma_f32 v[110:111], v[142:143], s[6:7], v[80:81] op_sel_hi:[1,0,0]
	v_pk_fma_f32 v[108:109], v[140:141], s[6:7], v[80:81] op_sel_hi:[1,0,0]
	v_pk_fma_f32 v[106:107], v[138:139], s[6:7], v[80:81] op_sel_hi:[1,0,0]
	v_pk_fma_f32 v[104:105], v[136:137], s[6:7], v[80:81] op_sel_hi:[1,0,0]
	v_pk_fma_f32 v[102:103], v[134:135], s[6:7], v[80:81] op_sel_hi:[1,0,0]
	v_pk_fma_f32 v[100:101], v[132:133], s[6:7], v[80:81] op_sel_hi:[1,0,0]
	v_pk_fma_f32 v[98:99], v[130:131], s[6:7], v[80:81] op_sel_hi:[1,0,0]
	v_pk_fma_f32 v[96:97], v[128:129], s[6:7], v[80:81] op_sel_hi:[1,0,0]
	v_pk_fma_f32 v[94:95], v[126:127], s[6:7], v[80:81] op_sel_hi:[1,0,0]
	v_pk_fma_f32 v[92:93], v[124:125], s[6:7], v[80:81] op_sel_hi:[1,0,0]
	v_pk_fma_f32 v[90:91], v[122:123], s[6:7], v[80:81] op_sel_hi:[1,0,0]
	v_pk_fma_f32 v[88:89], v[120:121], s[6:7], v[80:81] op_sel_hi:[1,0,0]
	v_pk_fma_f32 v[86:87], v[118:119], s[6:7], v[80:81] op_sel_hi:[1,0,0]
	v_pk_fma_f32 v[84:85], v[116:117], s[6:7], v[80:81] op_sel_hi:[1,0,0]
	v_pk_fma_f32 v[82:83], v[114:115], s[6:7], v[80:81] op_sel_hi:[1,0,0]
	v_pk_fma_f32 v[80:81], v[112:113], s[6:7], v[80:81] op_sel_hi:[1,0,0]

; __device__ __forceinline__ void partialSM(f32x16& p0, f32x16& p1, float& m_reg, float& mn, float& alpha, int kt0, int qpos, int qw, int hi, const float* tb2, float cL, float cR) {
;     ...
;   const int rel_hi = kt0 + 63 - qw, rel_lo = kt0 - (qw + 31);
;   if (rel_hi <= -91 || rel_lo >= 91) {
;     const float cm = ((rel_hi <= -91) ? cL : cR) - m_reg;
; #pragma unroll
;     for (int r = 0; r < 16; ++r) { p0[r] = fmaf(p0[r], C1, cm); p1[r] = fmaf(p1[r], C1, cm); }
.LBB0_328:
	s_andn2_b64 vcc, exec, s[0:1]
	s_cbranch_vccnz .LBB0_330
	s_cmpk_lt_i32 s66, 0xffa6
	s_cselect_b32 s69, s62, s63
	v_sub_f32_e32 v80, s69, v64
	v_pk_fma_f32 v[142:143], v[126:127], s[6:7], v[80:81] op_sel_hi:[1,0,0]
	v_pk_fma_f32 v[140:141], v[124:125], s[6:7], v[80:81] op_sel_hi:[1,0,0]
	v_pk_fma_f32 v[138:139], v[122:123], s[6:7], v[80:81] op_sel_hi:[1,0,0]
	v_pk_fma_f32 v[136:137], v[120:121], s[6:7], v[80:81] op_sel_hi:[1,0,0]
	v_pk_fma_f32 v[134:135], v[118:119], s[6:7], v[80:81] op_sel_hi:[1,0,0]
	v_pk_fma_f32 v[132:133], v[116:117], s[6:7], v[80:81] op_sel_hi:[1,0,0]
	v_pk_fma_f32 v[130:131], v[114:115], s[6:7], v[80:81] op_sel_hi:[1,0,0]
	v_pk_fma_f32 v[128:129], v[112:113], s[6:7], v[80:81] op_sel_hi:[1,0,0]
	v_pk_fma_f32 v[94:95], v[110:111], s[6:7], v[80:81] op_sel_hi:[1,0,0]
	v_pk_fma_f32 v[92:93], v[108:109], s[6:7], v[80:81] op_sel_hi:[1,0,0]
	v_pk_fma_f32 v[90:91], v[106:107], s[6:7], v[80:81] op_sel_hi:[1,0,0]
	v_pk_fma_f32 v[88:89], v[104:105], s[6:7], v[80:81] op_sel_hi:[1,0,0]
	v_pk_fma_f32 v[86:87], v[102:103], s[6:7], v[80:81] op_sel_hi:[1,0,0]
	v_pk_fma_f32 v[84:85], v[100:101], s[6:7], v[80:81] op_sel_hi:[1,0,0]
	v_pk_fma_f32 v[82:83], v[98:99], s[6:7], v[80:81] op_sel_hi:[1,0,0]
	v_pk_fma_f32 v[80:81], v[96:97], s[6:7], v[80:81] op_sel_hi:[1,0,0]

; __device__ __forceinline__ void partialSM(f32x16& p0, f32x16& p1, float& m_reg, float& mn, float& alpha, int kt0, int qpos, int qw, int hi, const float* tb2, float cL, float cR) {
;     ...
;   const int rel_hi = kt0 + 63 - qw, rel_lo = kt0 - (qw + 31);
;   if (rel_hi <= -91 || rel_lo >= 91) {
;     const float cm = ((rel_hi <= -91) ? cL : cR) - m_reg;
; #pragma unroll
;     for (int r = 0; r < 16; ++r) { p0[r] = fmaf(p0[r], C1, cm); p1[r] = fmaf(p1[r], C1, cm); }
.LBB0_334:
	s_andn2_b64 vcc, exec, s[26:27]
	s_cbranch_vccnz .LBB0_336
	s_add_i32 s5, s66, 64
	s_cmpk_lt_i32 s5, 0xffa6
	s_cselect_b32 s69, s62, s63
	v_sub_f32_e32 v80, s69, v64
	v_pk_fma_f32 v[110:111], v[142:143], s[6:7], v[80:81] op_sel_hi:[1,0,0]
	v_pk_fma_f32 v[108:109], v[140:141], s[6:7], v[80:81] op_sel_hi:[1,0,0]
	v_pk_fma_f32 v[106:107], v[138:139], s[6:7], v[80:81] op_sel_hi:[1,0,0]
	v_pk_fma_f32 v[104:105], v[136:137], s[6:7], v[80:81] op_sel_hi:[1,0,0]
	v_pk_fma_f32 v[102:103], v[134:135], s[6:7], v[80:81] op_sel_hi:[1,0,0]
	v_pk_fma_f32 v[100:101], v[132:133], s[6:7], v[80:81] op_sel_hi:[1,0,0]
	v_pk_fma_f32 v[98:99], v[130:131], s[6:7], v[80:81] op_sel_hi:[1,0,0]
	v_pk_fma_f32 v[96:97], v[128:129], s[6:7], v[80:81] op_sel_hi:[1,0,0]
	v_pk_fma_f32 v[94:95], v[126:127], s[6:7], v[80:81] op_sel_hi:[1,0,0]
	v_pk_fma_f32 v[92:93], v[124:125], s[6:7], v[80:81] op_sel_hi:[1,0,0]
	v_pk_fma_f32 v[90:91], v[122:123], s[6:7], v[80:81] op_sel_hi:[1,0,0]
	v_pk_fma_f32 v[88:89], v[120:121], s[6:7], v[80:81] op_sel_hi:[1,0,0]
	v_pk_fma_f32 v[86:87], v[118:119], s[6:7], v[80:81] op_sel_hi:[1,0,0]
	v_pk_fma_f32 v[84:85], v[116:117], s[6:7], v[80:81] op_sel_hi:[1,0,0]
	v_pk_fma_f32 v[82:83], v[114:115], s[6:7], v[80:81] op_sel_hi:[1,0,0]
	v_pk_fma_f32 v[80:81], v[112:113], s[6:7], v[80:81] op_sel_hi:[1,0,0]

; __device__ __forceinline__ void partialSM(f32x16& p0, f32x16& p1, float& m_reg, float& mn, float& alpha, int kt0, int qpos, int qw, int hi, const float* tb2, float cL, float cR) {
;     ...
;   const int rel_hi = kt0 + 63 - qw, rel_lo = kt0 - (qw + 31);
;   if (rel_hi <= -91 || rel_lo >= 91) {
;     const float cm = ((rel_hi <= -91) ? cL : cR) - m_reg;
; #pragma unroll
;     for (int r = 0; r < 16; ++r) { p0[r] = fmaf(p0[r], C1, cm); p1[r] = fmaf(p1[r], C1, cm); }
.LBB0_355:
	s_andn2_b64 vcc, exec, s[0:1]
	s_cbranch_vccnz .LBB0_357
	s_cmpk_lt_i32 s62, 0xffa6
	s_cselect_b32 s69, s54, s55
	v_sub_f32_e32 v128, s69, v0
	v_pk_fma_f32 v[94:95], v[126:127], s[6:7], v[128:129] op_sel_hi:[1,0,0]
	v_pk_fma_f32 v[92:93], v[124:125], s[6:7], v[128:129] op_sel_hi:[1,0,0]
	v_pk_fma_f32 v[90:91], v[122:123], s[6:7], v[128:129] op_sel_hi:[1,0,0]
	v_pk_fma_f32 v[88:89], v[120:121], s[6:7], v[128:129] op_sel_hi:[1,0,0]
	v_pk_fma_f32 v[86:87], v[118:119], s[6:7], v[128:129] op_sel_hi:[1,0,0]
	v_pk_fma_f32 v[84:85], v[116:117], s[6:7], v[128:129] op_sel_hi:[1,0,0]
	v_pk_fma_f32 v[82:83], v[114:115], s[6:7], v[128:129] op_sel_hi:[1,0,0]
	v_pk_fma_f32 v[80:81], v[112:113], s[6:7], v[128:129] op_sel_hi:[1,0,0]
	v_pk_fma_f32 v[142:143], v[110:111], s[6:7], v[128:129] op_sel_hi:[1,0,0]
	v_pk_fma_f32 v[140:141], v[108:109], s[6:7], v[128:129] op_sel_hi:[1,0,0]
	v_pk_fma_f32 v[138:139], v[106:107], s[6:7], v[128:129] op_sel_hi:[1,0,0]
	v_pk_fma_f32 v[136:137], v[104:105], s[6:7], v[128:129] op_sel_hi:[1,0,0]
	v_pk_fma_f32 v[134:135], v[102:103], s[6:7], v[128:129] op_sel_hi:[1,0,0]
	v_pk_fma_f32 v[132:133], v[100:101], s[6:7], v[128:129] op_sel_hi:[1,0,0]
	v_pk_fma_f32 v[130:131], v[98:99], s[6:7], v[128:129] op_sel_hi:[1,0,0]
	v_pk_fma_f32 v[128:129], v[96:97], s[6:7], v[128:129] op_sel_hi:[1,0,0]

; __device__ __forceinline__ void partialSM(f32x16& p0, f32x16& p1, float& m_reg, float& mn, float& alpha, int kt0, int qpos, int qw, int hi, const float* tb2, float cL, float cR) {
;     ...
;   const int rel_hi = kt0 + 63 - qw, rel_lo = kt0 - (qw + 31);
;   if (rel_hi <= -91 || rel_lo >= 91) {
;     const float cm = ((rel_hi <= -91) ? cL : cR) - m_reg;
; #pragma unroll
;     for (int r = 0; r < 16; ++r) { p0[r] = fmaf(p0[r], C1, cm); p1[r] = fmaf(p1[r], C1, cm); }
.LBB0_361:
	s_andn2_b64 vcc, exec, s[26:27]
	s_cbranch_vccnz .LBB0_363
	s_add_i32 s5, s62, 64
	s_cmpk_lt_i32 s5, 0xffa6
	s_cselect_b32 s69, s54, s55
	v_sub_f32_e32 v80, s69, v0
	v_pk_fma_f32 v[142:143], v[126:127], s[6:7], v[80:81] op_sel_hi:[1,0,0]
	v_pk_fma_f32 v[140:141], v[124:125], s[6:7], v[80:81] op_sel_hi:[1,0,0]
	v_pk_fma_f32 v[138:139], v[122:123], s[6:7], v[80:81] op_sel_hi:[1,0,0]
	v_pk_fma_f32 v[136:137], v[120:121], s[6:7], v[80:81] op_sel_hi:[1,0,0]
	v_pk_fma_f32 v[134:135], v[118:119], s[6:7], v[80:81] op_sel_hi:[1,0,0]
	v_pk_fma_f32 v[132:133], v[116:117], s[6:7], v[80:81] op_sel_hi:[1,0,0]
	v_pk_fma_f32 v[130:131], v[114:115], s[6:7], v[80:81] op_sel_hi:[1,0,0]
	v_pk_fma_f32 v[128:129], v[112:113], s[6:7], v[80:81] op_sel_hi:[1,0,0]
	v_pk_fma_f32 v[94:95], v[110:111], s[6:7], v[80:81] op_sel_hi:[1,0,0]
	v_pk_fma_f32 v[92:93], v[108:109], s[6:7], v[80:81] op_sel_hi:[1,0,0]
	v_pk_fma_f32 v[90:91], v[106:107], s[6:7], v[80:81] op_sel_hi:[1,0,0]
	v_pk_fma_f32 v[88:89], v[104:105], s[6:7], v[80:81] op_sel_hi:[1,0,0]
	v_pk_fma_f32 v[86:87], v[102:103], s[6:7], v[80:81] op_sel_hi:[1,0,0]
	v_pk_fma_f32 v[84:85], v[100:101], s[6:7], v[80:81] op_sel_hi:[1,0,0]
	v_pk_fma_f32 v[82:83], v[98:99], s[6:7], v[80:81] op_sel_hi:[1,0,0]
	v_pk_fma_f32 v[80:81], v[96:97], s[6:7], v[80:81] op_sel_hi:[1,0,0]

; __device__ __forceinline__ void partialSM(f32x16& p0, f32x16& p1, float& m_reg, float& mn, float& alpha, int kt0, int qpos, int qw, int hi, const float* tb2, float cL, float cR) {
;     ...
;   const int rel_hi = kt0 + 63 - qw, rel_lo = kt0 - (qw + 31);
;   if (rel_hi <= -91 || rel_lo >= 91) {
;     const float cm = ((rel_hi <= -91) ? cL : cR) - m_reg;
; #pragma unroll
;     for (int r = 0; r < 16; ++r) { p0[r] = fmaf(p0[r], C1, cm); p1[r] = fmaf(p1[r], C1, cm); }
.LBB0_380:
	s_andn2_b64 vcc, exec, s[0:1]
	s_cbranch_vccnz .LBB0_382
	s_cmpk_lt_i32 s48, 0xffa6
	s_cselect_b32 s69, s52, s53
	v_sub_f32_e32 v128, s69, v64
	v_pk_fma_f32 v[94:95], v[126:127], s[6:7], v[128:129] op_sel_hi:[1,0,0]
	v_pk_fma_f32 v[92:93], v[124:125], s[6:7], v[128:129] op_sel_hi:[1,0,0]
	v_pk_fma_f32 v[90:91], v[122:123], s[6:7], v[128:129] op_sel_hi:[1,0,0]
	v_pk_fma_f32 v[88:89], v[120:121], s[6:7], v[128:129] op_sel_hi:[1,0,0]
	v_pk_fma_f32 v[86:87], v[118:119], s[6:7], v[128:129] op_sel_hi:[1,0,0]
	v_pk_fma_f32 v[84:85], v[116:117], s[6:7], v[128:129] op_sel_hi:[1,0,0]
	v_pk_fma_f32 v[82:83], v[114:115], s[6:7], v[128:129] op_sel_hi:[1,0,0]
	v_pk_fma_f32 v[80:81], v[112:113], s[6:7], v[128:129] op_sel_hi:[1,0,0]
	v_pk_fma_f32 v[142:143], v[110:111], s[6:7], v[128:129] op_sel_hi:[1,0,0]
	v_pk_fma_f32 v[140:141], v[108:109], s[6:7], v[128:129] op_sel_hi:[1,0,0]
	v_pk_fma_f32 v[138:139], v[106:107], s[6:7], v[128:129] op_sel_hi:[1,0,0]
	v_pk_fma_f32 v[136:137], v[104:105], s[6:7], v[128:129] op_sel_hi:[1,0,0]
	v_pk_fma_f32 v[134:135], v[102:103], s[6:7], v[128:129] op_sel_hi:[1,0,0]
	v_pk_fma_f32 v[132:133], v[100:101], s[6:7], v[128:129] op_sel_hi:[1,0,0]
	v_pk_fma_f32 v[130:131], v[98:99], s[6:7], v[128:129] op_sel_hi:[1,0,0]
	v_pk_fma_f32 v[128:129], v[96:97], s[6:7], v[128:129] op_sel_hi:[1,0,0]

; __device__ __forceinline__ void partialSM(f32x16& p0, f32x16& p1, float& m_reg, float& mn, float& alpha, int kt0, int qpos, int qw, int hi, const float* tb2, float cL, float cR) {
;     ...
;   const int rel_hi = kt0 + 63 - qw, rel_lo = kt0 - (qw + 31);
;   if (rel_hi <= -91 || rel_lo >= 91) {
;     const float cm = ((rel_hi <= -91) ? cL : cR) - m_reg;
; #pragma unroll
;     for (int r = 0; r < 16; ++r) { p0[r] = fmaf(p0[r], C1, cm); p1[r] = fmaf(p1[r], C1, cm); }
.LBB0_386:
	s_andn2_b64 vcc, exec, s[26:27]
	s_cbranch_vccnz .LBB0_388
	s_add_i32 s5, s48, 64
	s_cmpk_lt_i32 s5, 0xffa6
	s_cselect_b32 s69, s52, s53
	v_sub_f32_e32 v80, s69, v64
	v_pk_fma_f32 v[142:143], v[126:127], s[6:7], v[80:81] op_sel_hi:[1,0,0]
	v_pk_fma_f32 v[140:141], v[124:125], s[6:7], v[80:81] op_sel_hi:[1,0,0]
	v_pk_fma_f32 v[138:139], v[122:123], s[6:7], v[80:81] op_sel_hi:[1,0,0]
	v_pk_fma_f32 v[136:137], v[120:121], s[6:7], v[80:81] op_sel_hi:[1,0,0]
	v_pk_fma_f32 v[134:135], v[118:119], s[6:7], v[80:81] op_sel_hi:[1,0,0]
	v_pk_fma_f32 v[132:133], v[116:117], s[6:7], v[80:81] op_sel_hi:[1,0,0]
	v_pk_fma_f32 v[130:131], v[114:115], s[6:7], v[80:81] op_sel_hi:[1,0,0]
	v_pk_fma_f32 v[128:129], v[112:113], s[6:7], v[80:81] op_sel_hi:[1,0,0]
	v_pk_fma_f32 v[94:95], v[110:111], s[6:7], v[80:81] op_sel_hi:[1,0,0]
	v_pk_fma_f32 v[92:93], v[108:109], s[6:7], v[80:81] op_sel_hi:[1,0,0]
	v_pk_fma_f32 v[90:91], v[106:107], s[6:7], v[80:81] op_sel_hi:[1,0,0]
	v_pk_fma_f32 v[88:89], v[104:105], s[6:7], v[80:81] op_sel_hi:[1,0,0]
	v_pk_fma_f32 v[86:87], v[102:103], s[6:7], v[80:81] op_sel_hi:[1,0,0]
	v_pk_fma_f32 v[84:85], v[100:101], s[6:7], v[80:81] op_sel_hi:[1,0,0]
	v_pk_fma_f32 v[82:83], v[98:99], s[6:7], v[80:81] op_sel_hi:[1,0,0]
	v_pk_fma_f32 v[80:81], v[96:97], s[6:7], v[80:81] op_sel_hi:[1,0,0]
